# hand-written grid barrier at the 5 seams after P0: all workgroups poll TOPGEN directly (no XGEN hop), acquire invalidate issued at arrival by wave 1, constant generation per seam; plus v_add3 address
# speedup vs baseline: 1.0161x; 1.0161x over previous
.LBB0_132:
	s_add_u32 s12, s54, 0x200
	s_addc_u32 s13, s55, 0
	s_add_u32 s18, s54, 0x1000
	s_addc_u32 s19, s55, 0
	s_add_u32 s20, s54, 0x1100
	s_addc_u32 s21, s55, 0
	s_add_u32 s22, s54, 0x1200
	s_addc_u32 s23, s55, 0
	s_add_u32 s24, s54, 0x1300
	s_mul_i32 s83, s35, s34
	v_readlane_b32 s0, v255, 0
	s_addc_u32 s25, s55, 0
	s_mul_i32 s83, s83, s0
	s_add_u32 s0, s54, 0x3400
	s_addc_u32 s1, s55, 0
	v_writelane_b32 v255, s0, 6
	s_barrier
	s_nop 0
	v_writelane_b32 v255, s1, 7
	s_add_u32 s0, s54, 0x3500
	s_addc_u32 s1, s55, 0
	s_waitcnt vmcnt(0)
	v_writelane_b32 v255, s0, 8
	s_barrier
	s_nop 0
	v_writelane_b32 v255, s1, 9
	s_mov_b64 s[4:5], exec
	v_readlane_b32 s0, v255, 1
	v_readlane_b32 s1, v255, 2
	s_and_b64 s[0:1], s[4:5], s[0:1]
	s_mov_b64 exec, s[0:1]
	s_cbranch_execz .Lgb2_others
	s_getreg_b32 s0, hwreg(HW_REG_XCC_ID, 0, 4)
	v_mov_b32_e32 v0, 0x23fc0
	ds_read_b64 v[2:3], v0
	s_and_b32 s0, s0, 15
	s_lshl_b32 s0, s0, 8
	s_add_u32 s6, s54, s0
	s_addc_u32 s7, s55, 0
	v_mov_b32_e32 v0, 0x1000
	v_mov_b32_e32 v1, 1
	global_atomic_add v1, v0, v1, s[6:7] offset:1024 sc0
	s_waitcnt lgkmcnt(0)
	v_readfirstlane_b32 s8, v2
	v_readfirstlane_b32 s9, v3
	s_mul_i32 s8, s8, 2
	s_mul_i32 s9, s9, 2
	v_mov_b32_e32 v0, 0x3000
	s_waitcnt vmcnt(0)
	v_readfirstlane_b32 s0, v1
	s_add_u32 s0, s0, 1
	s_cmp_lg_u32 s0, s8
	s_cbranch_scc1 .Lgb2_wait
	buffer_wbl2 sc1
	s_waitcnt vmcnt(0)
	v_mov_b32_e32 v1, 1
	global_atomic_add v1, v0, v1, s[54:55] offset:1024 sc0
	s_waitcnt vmcnt(0)
	v_readfirstlane_b32 s0, v1
	s_add_u32 s0, s0, 1
	s_cmp_lg_u32 s0, s9
	s_cbranch_scc1 .Lgb2_wait
	v_mov_b32_e32 v1, 1
	global_atomic_add v0, v1, s[54:55] offset:1280
	s_waitcnt vmcnt(0)
	s_branch .LBB0_184
.Lgb2_wait:
	s_mov_b32 s1, 0
.Lgb2_spin:
	global_load_dword v1, v0, s[54:55] offset:1280 sc1
	s_waitcnt vmcnt(0)
	v_readfirstlane_b32 s0, v1
	s_cmp_ge_u32 s0, 2
	s_cbranch_scc1 .LBB0_184
	s_sleep 1
	s_add_u32 s1, s1, 1
	s_cmp_lt_u32 s1, 0x40000
	s_cbranch_scc1 .Lgb2_spin
	s_branch .LBB0_184
.Lgb2_others:
	v_readfirstlane_b32 s0, v252
	s_cmp_lg_u32 s0, 64
	s_cbranch_scc1 .LBB0_184
	s_mov_b64 exec, 1
	buffer_inv sc1
	s_waitcnt vmcnt(0)

.LBB0_265:
	s_waitcnt vmcnt(0)
	s_waitcnt vmcnt(0) lgkmcnt(0)
	s_barrier
	s_mov_b64 s[4:5], exec
	v_readlane_b32 s0, v255, 1
	v_readlane_b32 s1, v255, 2
	s_and_b64 s[0:1], s[4:5], s[0:1]
	s_mov_b64 exec, s[0:1]
	s_cbranch_execz .Lgb3_others
	s_getreg_b32 s0, hwreg(HW_REG_XCC_ID, 0, 4)
	v_mov_b32_e32 v0, 0x23fc0
	ds_read_b64 v[2:3], v0
	s_and_b32 s0, s0, 15
	s_lshl_b32 s0, s0, 8
	s_add_u32 s6, s54, s0
	s_addc_u32 s7, s55, 0
	v_mov_b32_e32 v0, 0x1000
	v_mov_b32_e32 v1, 1
	global_atomic_add v1, v0, v1, s[6:7] offset:1024 sc0
	s_waitcnt lgkmcnt(0)
	v_readfirstlane_b32 s8, v2
	v_readfirstlane_b32 s9, v3
	s_mul_i32 s8, s8, 3
	s_mul_i32 s9, s9, 3
	v_mov_b32_e32 v0, 0x3000
	s_waitcnt vmcnt(0)
	v_readfirstlane_b32 s0, v1
	s_add_u32 s0, s0, 1
	s_cmp_lg_u32 s0, s8
	s_cbranch_scc1 .Lgb3_wait
	buffer_wbl2 sc1
	s_waitcnt vmcnt(0)
	v_mov_b32_e32 v1, 1
	global_atomic_add v1, v0, v1, s[54:55] offset:1024 sc0
	s_waitcnt vmcnt(0)
	v_readfirstlane_b32 s0, v1
	s_add_u32 s0, s0, 1
	s_cmp_lg_u32 s0, s9
	s_cbranch_scc1 .Lgb3_wait
	v_mov_b32_e32 v1, 1
	global_atomic_add v0, v1, s[54:55] offset:1280
	s_waitcnt vmcnt(0)
	s_branch .LBB0_317

.Lgb3_spin:
	global_load_dword v1, v0, s[54:55] offset:1280 sc1
	s_waitcnt vmcnt(0)
	v_readfirstlane_b32 s0, v1
	s_cmp_ge_u32 s0, 3
	s_cbranch_scc1 .LBB0_317
	s_sleep 1
	s_add_u32 s1, s1, 1
	s_cmp_lt_u32 s1, 0x40000
	s_cbranch_scc1 .Lgb3_spin
	s_branch .LBB0_317

.LBB0_361:
	s_add_i32 s0, s95, 2
	s_cmp_lt_u32 s0, s89
	s_cbranch_scc0 .Lat_tw_a
	s_waitcnt vmcnt(8)
.LBB0_369:
	s_barrier
	s_add_i32 s0, s93, s95
	s_add_i32 s1, s95, 3
	s_cmp_lt_u32 s1, s89
	s_cbranch_scc0 .LBB0_373
	s_add_i32 s4, s0, 3
	s_lshr_b32 s5, s4, 2
	s_and_b32 s4, s4, 3
	s_cmp_lt_u32 s1, s87
	s_cselect_b32 s5, s69, s5
	s_cselect_b32 s1, s1, s4
	s_lshl_b32 s4, s5, 8
	s_lshl_b32 s1, s1, 6
	s_add_i32 s46, s4, s1
	s_add_i32 s1, s90, 0x18000
	s_and_b32 s1, s1, 0x18000
	s_lshl_b64 s[4:5], s[46:47], 8
	s_add_i32 s1, s88, s1
	s_add_u32 s14, s82, s4
	s_addc_u32 s15, s84, s5
	s_add_u32 s4, s85, s4
	s_addc_u32 s5, s86, s5
	s_mov_b32 m0, s1
	v_lshl_add_u64 v[48:49], s[14:15], 0, v[96:97]
	global_load_lds_dwordx4 v[48:49], off
	s_add_i32 m0, s1, 0x4000
	v_lshl_add_u64 v[48:49], s[4:5], 0, v[98:99]
	global_load_lds_dwordx4 v[48:49], off
	s_add_i32 m0, s1, 0x400
	v_lshl_add_u64 v[48:49], s[14:15], 0, v[100:101]
	global_load_lds_dwordx4 v[48:49], off
	s_add_i32 m0, s1, 0x4400
	v_lshl_add_u64 v[48:49], s[4:5], 0, v[102:103]
	global_load_lds_dwordx4 v[48:49], off
.LBB0_373:
	s_lshr_b32 s4, s0, 2
	s_cmp_lt_u32 s95, s87
	s_cselect_b64 s[60:61], -1, 0
	s_cselect_b32 s0, s69, s4
	v_lshrrev_b32_e32 v48, s0, v125
	v_and_b32_e32 v48, 1, v48
	v_cmp_eq_u32_e64 s[4:5], 1, v48
	s_cbranch_scc1 .Lat_own_a
	s_nop 1
	s_cmp_lg_u64 s[4:5], 0
	s_cbranch_scc0 .LBB0_360
	s_branch .LBB0_378
.Lat_tw_a:
	s_add_i32 s0, s95, 1
	s_cmp_lt_u32 s0, s89
	s_cbranch_scc0 .Lat_w0_a
	s_waitcnt vmcnt(4)
	s_branch .LBB0_369
.Lat_w0_a:
	s_waitcnt vmcnt(0)
	s_branch .LBB0_369
.Lat_own_a:
	s_sub_i32 s0, s94, 63
	s_cmp_le_i32 s0, s91
	s_cbranch_scc0 .LBB0_360
.LBB0_378:
	s_and_b32 s0, s90, 0x18000
	v_add3_u32 v60, s0, v110, v109
	v_add3_u32 v76, s0, v111, v109
	v_add3_u32 v92, s0, v112, v109
	v_add3_u32 v126, s0, v113, v109
	ds_read_b128 v[48:51], v60
	ds_read_b128 v[52:55], v60 offset:4096
	ds_read_b128 v[56:59], v60 offset:8192
	ds_read_b128 v[60:63], v60 offset:12288
	ds_read_b128 v[64:67], v76
	ds_read_b128 v[68:71], v76 offset:4096
	ds_read_b128 v[72:75], v76 offset:8192
	ds_read_b128 v[76:79], v76 offset:12288
	ds_read_b128 v[80:83], v92
	ds_read_b128 v[84:87], v92 offset:4096
	ds_read_b128 v[88:91], v92 offset:8192
	ds_read_b128 v[92:95], v92 offset:12288
	ds_read_b128 v[132:135], v126
	ds_read_b128 v[136:139], v126 offset:4096
	ds_read_b128 v[140:143], v126 offset:8192
	ds_read_b128 v[144:147], v126 offset:12288
	s_waitcnt lgkmcnt(14)
	v_mfma_f32_16x16x32_bf16 v[48:51], v[48:51], v[0:3], 0
	v_mfma_f32_16x16x32_bf16 v[52:55], v[52:55], v[0:3], 0
	s_waitcnt lgkmcnt(12)
	v_mfma_f32_16x16x32_bf16 v[60:63], v[60:63], v[0:3], 0
	s_waitcnt lgkmcnt(11)
	v_mfma_f32_16x16x32_bf16 v[48:51], v[64:67], v[4:7], v[48:51]
	v_mfma_f32_16x16x32_bf16 v[56:59], v[56:59], v[0:3], 0
	s_waitcnt lgkmcnt(10)
	v_mfma_f32_16x16x32_bf16 v[52:55], v[68:71], v[4:7], v[52:55]
	s_waitcnt lgkmcnt(8)
	v_mfma_f32_16x16x32_bf16 v[60:63], v[76:79], v[4:7], v[60:63]
	s_waitcnt lgkmcnt(7)
	v_mfma_f32_16x16x32_bf16 v[68:71], v[80:83], v[8:11], v[48:51]
	v_mfma_f32_16x16x32_bf16 v[64:67], v[72:75], v[4:7], v[56:59]
	v_add3_u32 v128, s0, v118, v115
	s_waitcnt lgkmcnt(6)
	v_mfma_f32_16x16x32_bf16 v[76:79], v[84:87], v[8:11], v[52:55]
	v_add3_u32 v126, s0, v116, v115
	s_waitcnt lgkmcnt(4)
	v_mfma_f32_16x16x32_bf16 v[148:151], v[92:95], v[8:11], v[60:63]
	v_add3_u32 v130, s0, v120, v115
	v_add3_u32 v127, s0, v117, v115
	s_waitcnt lgkmcnt(3)
	v_mfma_f32_16x16x32_bf16 v[92:95], v[132:135], v[12:15], v[68:71]
	ds_read_b64_tr_b16 v[56:57], v126 offset:16384
	ds_read_b64_tr_b16 v[58:59], v126 offset:20480
	ds_read_b64_tr_b16 v[48:49], v127 offset:16384
	ds_read_b64_tr_b16 v[50:51], v127 offset:20480
	v_mfma_f32_16x16x32_bf16 v[80:83], v[88:91], v[8:11], v[64:67]
	v_add3_u32 v132, s0, v122, v115
	v_add3_u32 v129, s0, v119, v115
	ds_read_b64_tr_b16 v[64:65], v128 offset:16384
	ds_read_b64_tr_b16 v[66:67], v128 offset:20480
	ds_read_b64_tr_b16 v[52:53], v129 offset:16384
	ds_read_b64_tr_b16 v[54:55], v129 offset:20480
	v_add3_u32 v131, s0, v121, v115
	ds_read_b64_tr_b16 v[72:73], v130 offset:16384
	ds_read_b64_tr_b16 v[74:75], v130 offset:20480
	ds_read_b64_tr_b16 v[60:61], v131 offset:16384
	ds_read_b64_tr_b16 v[62:63], v131 offset:20480
	s_waitcnt lgkmcnt(14)
	v_mfma_f32_16x16x32_bf16 v[88:91], v[136:139], v[12:15], v[76:79]
	v_add3_u32 v133, s0, v123, v115
	s_nop 1
	ds_read_b64_tr_b16 v[76:77], v132 offset:16384
	ds_read_b64_tr_b16 v[78:79], v132 offset:20480
	ds_read_b64_tr_b16 v[68:69], v133 offset:16384
	ds_read_b64_tr_b16 v[70:71], v133 offset:20480
	s_waitcnt lgkmcnt(14)
	v_mfma_f32_16x16x32_bf16 v[84:87], v[140:143], v[12:15], v[80:83]
	v_mfma_f32_16x16x32_bf16 v[80:83], v[144:147], v[12:15], v[148:151]
	s_andn2_b64 vcc, exec, s[60:61]
	s_cbranch_vccnz .LBB0_381
	s_cmp_le_i32 s94, s80
	s_cbranch_scc1 .LBB0_381
	v_add_u32_e32 v134, s94, v114
	v_subrev_u32_e32 v135, 63, v134
	v_cmp_gt_i32_e32 vcc, v135, v104
	s_nop 1
	v_cndmask_b32_e32 v136, v92, v106, vcc
	v_cmp_lt_i32_e32 vcc, v135, v104
	v_subrev_u32_e32 v135, 61, v134
	s_nop 0
	v_cndmask_b32_e32 v92, v136, v92, vcc
	v_cndmask_b32_e32 v93, v106, v93, vcc
	v_cmp_le_i32_e32 vcc, v135, v104
	v_subrev_u32_e32 v135, 60, v134
	s_nop 0
	v_cndmask_b32_e32 v94, v106, v94, vcc
	v_cmp_le_i32_e32 vcc, v135, v104
	v_subrev_u32_e32 v135, 47, v134
	s_nop 0
	v_cndmask_b32_e32 v95, v106, v95, vcc
	v_cmp_le_i32_e32 vcc, v135, v104
	v_subrev_u32_e32 v135, 46, v134
	s_nop 0
	v_cndmask_b32_e32 v88, v106, v88, vcc
	v_cmp_le_i32_e32 vcc, v135, v104
	v_subrev_u32_e32 v135, 45, v134
	s_nop 0
	v_cndmask_b32_e32 v89, v106, v89, vcc
	v_cmp_le_i32_e32 vcc, v135, v104
	v_subrev_u32_e32 v135, 44, v134
	s_nop 0
	v_cndmask_b32_e32 v90, v106, v90, vcc
	v_cmp_le_i32_e32 vcc, v135, v104
	v_subrev_u32_e32 v135, 31, v134
	s_nop 0
	v_cndmask_b32_e32 v91, v106, v91, vcc
	v_cmp_le_i32_e32 vcc, v135, v104
	v_subrev_u32_e32 v135, 30, v134
	s_nop 0
	v_cndmask_b32_e32 v84, v106, v84, vcc
	v_cmp_le_i32_e32 vcc, v135, v104
	v_subrev_u32_e32 v135, 29, v134
	s_nop 0
	v_cndmask_b32_e32 v85, v106, v85, vcc
	v_cmp_le_i32_e32 vcc, v135, v104
	v_subrev_u32_e32 v135, 28, v134
	s_nop 0
	v_cndmask_b32_e32 v86, v106, v86, vcc
	v_cmp_le_i32_e32 vcc, v135, v104
	v_add_u32_e32 v135, -15, v134
	s_nop 0
	v_cndmask_b32_e32 v87, v106, v87, vcc
	v_cmp_le_i32_e32 vcc, v135, v104
	v_add_u32_e32 v135, -14, v134
	s_nop 0
	v_cndmask_b32_e32 v80, v106, v80, vcc
	v_cmp_le_i32_e32 vcc, v135, v104
	v_add_u32_e32 v135, -13, v134
	v_add_u32_e32 v134, -12, v134
	v_cndmask_b32_e32 v81, v106, v81, vcc
	v_cmp_le_i32_e32 vcc, v135, v104
	s_nop 1
	v_cndmask_b32_e32 v82, v106, v82, vcc
	v_cmp_le_i32_e32 vcc, v134, v104
	s_nop 1
	v_cndmask_b32_e32 v83, v106, v83, vcc
.LBB0_381:
	v_max3_f32 v134, v92, v93, v94
	s_nop 5
	v_max_f32_e32 v135, v83, v83
	v_max3_f32 v134, v134, v95, v88
	s_or_b64 s[4:5], s[60:61], s[4:5]
	v_max3_f32 v134, v134, v89, v90
	v_max3_f32 v134, v134, v91, v84
	v_max3_f32 v134, v134, v85, v86
	v_max3_f32 v134, v134, v87, v80
	v_max3_f32 v134, v134, v81, v82
	v_max_f32_e32 v134, v134, v134
	v_max_f32_e32 v134, v134, v135
	v_cndmask_b32_e64 v134, v106, v134, s[4:5]
	ds_swizzle_b32 v135, v134 offset:swizzle(SWAP,16)
	s_waitcnt lgkmcnt(0)
	v_max_f32_e32 v135, v135, v135
	v_max_f32_e32 v134, v134, v135
	ds_bpermute_b32 v135, v105, v134
	s_waitcnt lgkmcnt(0)
	v_max_f32_e32 v135, v135, v135
	v_max_f32_e32 v134, v134, v135
	v_mul_f32_e32 v134, 0x3e0293ee, v134
	v_add_f32_e32 v135, 0x41000000, v108
	v_cmp_gt_f32_e32 vcc, v134, v135
	s_cbranch_vccz .LBB0_359
	v_max_f32_e32 v134, v134, v134
	v_max_f32_e32 v135, v108, v108
	v_max_f32_e32 v134, v135, v134
	v_sub_f32_e32 v108, v108, v134
	v_exp_f32_e32 v108, v108
	s_nop 0
	v_pk_mul_f32 v[42:43], v[42:43], v[108:109] op_sel_hi:[1,0]
	v_pk_mul_f32 v[40:41], v[40:41], v[108:109] op_sel_hi:[1,0]
	v_pk_mul_f32 v[46:47], v[46:47], v[108:109] op_sel_hi:[1,0]
	v_pk_mul_f32 v[44:45], v[44:45], v[108:109] op_sel_hi:[1,0]
	v_pk_mul_f32 v[38:39], v[38:39], v[108:109] op_sel_hi:[1,0]
	v_pk_mul_f32 v[36:37], v[36:37], v[108:109] op_sel_hi:[1,0]
	v_pk_mul_f32 v[34:35], v[34:35], v[108:109] op_sel_hi:[1,0]
	v_pk_mul_f32 v[32:33], v[32:33], v[108:109] op_sel_hi:[1,0]
	v_pk_mul_f32 v[30:31], v[30:31], v[108:109] op_sel_hi:[1,0]
	v_pk_mul_f32 v[28:29], v[28:29], v[108:109] op_sel_hi:[1,0]
	v_pk_mul_f32 v[26:27], v[26:27], v[108:109] op_sel_hi:[1,0]
	v_pk_mul_f32 v[24:25], v[24:25], v[108:109] op_sel_hi:[1,0]
	v_pk_mul_f32 v[22:23], v[22:23], v[108:109] op_sel_hi:[1,0]
	v_pk_mul_f32 v[20:21], v[20:21], v[108:109] op_sel_hi:[1,0]
	v_pk_mul_f32 v[18:19], v[18:19], v[108:109] op_sel_hi:[1,0]
	v_pk_mul_f32 v[16:17], v[16:17], v[108:109] op_sel_hi:[1,0]
	v_mul_f32_e32 v124, v124, v108
	v_mov_b32_e32 v108, v134
	s_branch .LBB0_359

.LBB0_415:
	s_add_i32 s0, s85, 2
	s_cmp_lt_u32 s0, s75
	s_cbranch_scc0 .Lat_tw_b
	s_waitcnt vmcnt(8)
.LBB0_423:
	s_barrier
	s_add_i32 s0, s82, s85
	s_add_i32 s1, s85, 3
	s_cmp_lt_u32 s1, s75
	s_cbranch_scc0 .LBB0_427
	s_add_i32 s4, s0, 3
	s_lshr_b32 s5, s4, 2
	s_and_b32 s4, s4, 3
	s_cmp_lt_u32 s1, s68
	s_cselect_b32 s5, s80, s5
	s_cselect_b32 s1, s1, s4
	s_lshl_b32 s4, s5, 8
	s_lshl_b32 s1, s1, 6
	s_add_i32 s46, s4, s1
	s_add_i32 s1, s78, 0x18000
	s_and_b32 s1, s1, 0x18000
	s_lshl_b64 s[4:5], s[46:47], 8
	s_add_i32 s1, s69, s1
	s_add_u32 s14, s59, s4
	s_addc_u32 s15, s65, s5
	s_add_u32 s4, s66, s4
	s_addc_u32 s5, s67, s5
	s_mov_b32 m0, s1
	v_lshl_add_u64 v[48:49], s[14:15], 0, v[96:97]
	global_load_lds_dwordx4 v[48:49], off
	s_add_i32 m0, s1, 0x4000
	v_lshl_add_u64 v[48:49], s[4:5], 0, v[98:99]
	global_load_lds_dwordx4 v[48:49], off
	s_add_i32 m0, s1, 0x400
	v_lshl_add_u64 v[48:49], s[14:15], 0, v[100:101]
	global_load_lds_dwordx4 v[48:49], off
	s_add_i32 m0, s1, 0x4400
	v_lshl_add_u64 v[48:49], s[4:5], 0, v[102:103]
	global_load_lds_dwordx4 v[48:49], off
.LBB0_427:
	s_lshr_b32 s4, s0, 2
	s_cmp_lt_u32 s85, s68
	s_cselect_b64 s[52:53], -1, 0
	s_cselect_b32 s0, s80, s4
	v_lshrrev_b32_e32 v48, s0, v125
	v_and_b32_e32 v48, 1, v48
	v_cmp_eq_u32_e64 s[4:5], 1, v48
	s_cbranch_scc1 .Lat_own_b
	s_nop 1
	s_cmp_lg_u64 s[4:5], 0
	s_cbranch_scc0 .LBB0_414
	s_branch .LBB0_432
.Lat_tw_b:
	s_add_i32 s0, s85, 1
	s_cmp_lt_u32 s0, s75
	s_cbranch_scc0 .Lat_w0_b
	s_waitcnt vmcnt(4)
	s_branch .LBB0_423

.Lat_own_b:
	s_sub_i32 s0, s84, 63
	s_cmp_le_i32 s0, s79
	s_cbranch_scc0 .LBB0_414
.LBB0_432:
	s_and_b32 s0, s78, 0x18000
	v_add3_u32 v60, s0, v110, v109
	v_add3_u32 v76, s0, v111, v109
	v_add3_u32 v92, s0, v112, v109
	v_add3_u32 v126, s0, v113, v109
	ds_read_b128 v[48:51], v60
	ds_read_b128 v[52:55], v60 offset:4096
	ds_read_b128 v[56:59], v60 offset:8192
	ds_read_b128 v[60:63], v60 offset:12288
	ds_read_b128 v[64:67], v76
	ds_read_b128 v[68:71], v76 offset:4096
	ds_read_b128 v[72:75], v76 offset:8192
	ds_read_b128 v[76:79], v76 offset:12288
	ds_read_b128 v[80:83], v92
	ds_read_b128 v[84:87], v92 offset:4096
	ds_read_b128 v[88:91], v92 offset:8192
	ds_read_b128 v[92:95], v92 offset:12288
	ds_read_b128 v[132:135], v126
	ds_read_b128 v[136:139], v126 offset:4096
	ds_read_b128 v[140:143], v126 offset:8192
	ds_read_b128 v[144:147], v126 offset:12288
	s_waitcnt vmcnt(3) lgkmcnt(14)
	v_mfma_f32_16x16x32_bf16 v[48:51], v[48:51], v[0:3], 0
	v_mfma_f32_16x16x32_bf16 v[52:55], v[52:55], v[0:3], 0
	s_waitcnt lgkmcnt(12)
	v_mfma_f32_16x16x32_bf16 v[60:63], v[60:63], v[0:3], 0
	s_waitcnt vmcnt(2) lgkmcnt(11)
	v_mfma_f32_16x16x32_bf16 v[48:51], v[64:67], v[4:7], v[48:51]
	v_mfma_f32_16x16x32_bf16 v[56:59], v[56:59], v[0:3], 0
	s_waitcnt lgkmcnt(10)
	v_mfma_f32_16x16x32_bf16 v[52:55], v[68:71], v[4:7], v[52:55]
	s_waitcnt lgkmcnt(8)
	v_mfma_f32_16x16x32_bf16 v[60:63], v[76:79], v[4:7], v[60:63]
	s_waitcnt vmcnt(1) lgkmcnt(7)
	v_mfma_f32_16x16x32_bf16 v[68:71], v[80:83], v[8:11], v[48:51]
	v_mfma_f32_16x16x32_bf16 v[64:67], v[72:75], v[4:7], v[56:59]
	v_add3_u32 v128, s0, v118, v115
	s_waitcnt lgkmcnt(6)
	v_mfma_f32_16x16x32_bf16 v[76:79], v[84:87], v[8:11], v[52:55]
	v_add3_u32 v126, s0, v116, v115
	s_waitcnt lgkmcnt(4)
	v_mfma_f32_16x16x32_bf16 v[148:151], v[92:95], v[8:11], v[60:63]
	v_add3_u32 v130, s0, v120, v115
	v_add3_u32 v127, s0, v117, v115
	s_waitcnt vmcnt(0) lgkmcnt(3)
	v_mfma_f32_16x16x32_bf16 v[92:95], v[132:135], v[12:15], v[68:71]
	ds_read_b64_tr_b16 v[56:57], v126 offset:16384
	ds_read_b64_tr_b16 v[58:59], v126 offset:20480
	ds_read_b64_tr_b16 v[48:49], v127 offset:16384
	ds_read_b64_tr_b16 v[50:51], v127 offset:20480
	v_mfma_f32_16x16x32_bf16 v[80:83], v[88:91], v[8:11], v[64:67]
	v_add3_u32 v132, s0, v122, v115
	v_add3_u32 v129, s0, v119, v115
	ds_read_b64_tr_b16 v[64:65], v128 offset:16384
	ds_read_b64_tr_b16 v[66:67], v128 offset:20480
	ds_read_b64_tr_b16 v[52:53], v129 offset:16384
	ds_read_b64_tr_b16 v[54:55], v129 offset:20480
	v_add3_u32 v131, s0, v121, v115
	ds_read_b64_tr_b16 v[72:73], v130 offset:16384
	ds_read_b64_tr_b16 v[74:75], v130 offset:20480
	ds_read_b64_tr_b16 v[60:61], v131 offset:16384
	ds_read_b64_tr_b16 v[62:63], v131 offset:20480
	s_waitcnt lgkmcnt(14)
	v_mfma_f32_16x16x32_bf16 v[88:91], v[136:139], v[12:15], v[76:79]
	v_add3_u32 v133, s0, v123, v115
	s_nop 1
	ds_read_b64_tr_b16 v[76:77], v132 offset:16384
	ds_read_b64_tr_b16 v[78:79], v132 offset:20480
	ds_read_b64_tr_b16 v[68:69], v133 offset:16384
	ds_read_b64_tr_b16 v[70:71], v133 offset:20480
	s_waitcnt lgkmcnt(14)
	v_mfma_f32_16x16x32_bf16 v[84:87], v[140:143], v[12:15], v[80:83]
	v_mfma_f32_16x16x32_bf16 v[80:83], v[144:147], v[12:15], v[148:151]
	s_andn2_b64 vcc, exec, s[52:53]
	s_cbranch_vccnz .LBB0_435
	s_cmp_le_i32 s84, s64
	s_cbranch_scc1 .LBB0_435
	v_add_u32_e32 v134, s84, v114
	v_subrev_u32_e32 v135, 63, v134
	v_cmp_gt_i32_e32 vcc, v135, v104
	s_nop 1
	v_cndmask_b32_e32 v136, v92, v106, vcc
	v_cmp_lt_i32_e32 vcc, v135, v104
	v_subrev_u32_e32 v135, 61, v134
	s_nop 0
	v_cndmask_b32_e32 v92, v136, v92, vcc
	v_cndmask_b32_e32 v93, v106, v93, vcc
	v_cmp_le_i32_e32 vcc, v135, v104
	v_subrev_u32_e32 v135, 60, v134
	s_nop 0
	v_cndmask_b32_e32 v94, v106, v94, vcc
	v_cmp_le_i32_e32 vcc, v135, v104
	v_subrev_u32_e32 v135, 47, v134
	s_nop 0
	v_cndmask_b32_e32 v95, v106, v95, vcc
	v_cmp_le_i32_e32 vcc, v135, v104
	v_subrev_u32_e32 v135, 46, v134
	s_nop 0
	v_cndmask_b32_e32 v88, v106, v88, vcc
	v_cmp_le_i32_e32 vcc, v135, v104
	v_subrev_u32_e32 v135, 45, v134
	s_nop 0
	v_cndmask_b32_e32 v89, v106, v89, vcc
	v_cmp_le_i32_e32 vcc, v135, v104
	v_subrev_u32_e32 v135, 44, v134
	s_nop 0
	v_cndmask_b32_e32 v90, v106, v90, vcc
	v_cmp_le_i32_e32 vcc, v135, v104
	v_subrev_u32_e32 v135, 31, v134
	s_nop 0
	v_cndmask_b32_e32 v91, v106, v91, vcc
	v_cmp_le_i32_e32 vcc, v135, v104
	v_subrev_u32_e32 v135, 30, v134
	s_nop 0
	v_cndmask_b32_e32 v84, v106, v84, vcc
	v_cmp_le_i32_e32 vcc, v135, v104
	v_subrev_u32_e32 v135, 29, v134
	s_nop 0
	v_cndmask_b32_e32 v85, v106, v85, vcc
	v_cmp_le_i32_e32 vcc, v135, v104
	v_subrev_u32_e32 v135, 28, v134
	s_nop 0
	v_cndmask_b32_e32 v86, v106, v86, vcc
	v_cmp_le_i32_e32 vcc, v135, v104
	v_add_u32_e32 v135, -15, v134
	s_nop 0
	v_cndmask_b32_e32 v87, v106, v87, vcc
	v_cmp_le_i32_e32 vcc, v135, v104
	v_add_u32_e32 v135, -14, v134
	s_nop 0
	v_cndmask_b32_e32 v80, v106, v80, vcc
	v_cmp_le_i32_e32 vcc, v135, v104
	v_add_u32_e32 v135, -13, v134
	v_add_u32_e32 v134, -12, v134
	v_cndmask_b32_e32 v81, v106, v81, vcc
	v_cmp_le_i32_e32 vcc, v135, v104
	s_nop 1
	v_cndmask_b32_e32 v82, v106, v82, vcc
	v_cmp_le_i32_e32 vcc, v134, v104
	s_nop 1
	v_cndmask_b32_e32 v83, v106, v83, vcc
.LBB0_435:
	v_max3_f32 v134, v92, v93, v94
	s_nop 5
	v_max_f32_e32 v135, v83, v83
	v_max3_f32 v134, v134, v95, v88
	s_or_b64 s[4:5], s[52:53], s[4:5]
	v_max3_f32 v134, v134, v89, v90
	v_max3_f32 v134, v134, v91, v84
	v_max3_f32 v134, v134, v85, v86
	v_max3_f32 v134, v134, v87, v80
	v_max3_f32 v134, v134, v81, v82
	v_max_f32_e32 v134, v134, v134
	v_max_f32_e32 v134, v134, v135
	v_cndmask_b32_e64 v134, v106, v134, s[4:5]
	ds_swizzle_b32 v135, v134 offset:swizzle(SWAP,16)
	s_waitcnt lgkmcnt(0)
	v_max_f32_e32 v135, v135, v135
	v_max_f32_e32 v134, v134, v135
	ds_bpermute_b32 v135, v105, v134
	s_waitcnt lgkmcnt(0)
	v_max_f32_e32 v135, v135, v135
	v_max_f32_e32 v134, v134, v135
	v_mul_f32_e32 v134, 0x3e0293ee, v134
	v_add_f32_e32 v135, 0x41000000, v108
	v_cmp_gt_f32_e32 vcc, v134, v135
	s_cbranch_vccz .LBB0_413
	v_max_f32_e32 v134, v134, v134
	v_max_f32_e32 v135, v108, v108
	v_max_f32_e32 v134, v135, v134
	v_sub_f32_e32 v108, v108, v134
	v_exp_f32_e32 v108, v108
	s_nop 0
	v_pk_mul_f32 v[42:43], v[42:43], v[108:109] op_sel_hi:[1,0]
	v_pk_mul_f32 v[40:41], v[40:41], v[108:109] op_sel_hi:[1,0]
	v_pk_mul_f32 v[46:47], v[46:47], v[108:109] op_sel_hi:[1,0]
	v_pk_mul_f32 v[44:45], v[44:45], v[108:109] op_sel_hi:[1,0]
	v_pk_mul_f32 v[38:39], v[38:39], v[108:109] op_sel_hi:[1,0]
	v_pk_mul_f32 v[36:37], v[36:37], v[108:109] op_sel_hi:[1,0]
	v_pk_mul_f32 v[34:35], v[34:35], v[108:109] op_sel_hi:[1,0]
	v_pk_mul_f32 v[32:33], v[32:33], v[108:109] op_sel_hi:[1,0]
	v_pk_mul_f32 v[30:31], v[30:31], v[108:109] op_sel_hi:[1,0]
	v_pk_mul_f32 v[28:29], v[28:29], v[108:109] op_sel_hi:[1,0]
	v_pk_mul_f32 v[26:27], v[26:27], v[108:109] op_sel_hi:[1,0]
	v_pk_mul_f32 v[24:25], v[24:25], v[108:109] op_sel_hi:[1,0]
	v_pk_mul_f32 v[22:23], v[22:23], v[108:109] op_sel_hi:[1,0]
	v_pk_mul_f32 v[20:21], v[20:21], v[108:109] op_sel_hi:[1,0]
	v_pk_mul_f32 v[18:19], v[18:19], v[108:109] op_sel_hi:[1,0]
	v_pk_mul_f32 v[16:17], v[16:17], v[108:109] op_sel_hi:[1,0]
	v_mul_f32_e32 v124, v124, v108
	v_mov_b32_e32 v108, v134
	s_branch .LBB0_413

.LBB0_618:
	s_waitcnt vmcnt(0)
	s_barrier
	s_mov_b64 s[4:5], exec
	v_readlane_b32 s0, v255, 1
	v_readlane_b32 s1, v255, 2
	s_and_b64 s[0:1], s[4:5], s[0:1]
	s_mov_b64 exec, s[0:1]
	s_cbranch_execz .Lgb4_others
	s_getreg_b32 s0, hwreg(HW_REG_XCC_ID, 0, 4)
	v_mov_b32_e32 v0, 0x23fc0
	ds_read_b64 v[2:3], v0
	s_and_b32 s0, s0, 15
	s_lshl_b32 s0, s0, 8
	s_add_u32 s6, s54, s0
	s_addc_u32 s7, s55, 0
	v_mov_b32_e32 v0, 0x1000
	v_mov_b32_e32 v1, 1
	global_atomic_add v1, v0, v1, s[6:7] offset:1024 sc0
	s_waitcnt lgkmcnt(0)
	v_readfirstlane_b32 s8, v2
	v_readfirstlane_b32 s9, v3
	s_mul_i32 s8, s8, 4
	s_mul_i32 s9, s9, 4
	v_mov_b32_e32 v0, 0x3000
	s_waitcnt vmcnt(0)
	v_readfirstlane_b32 s0, v1
	s_add_u32 s0, s0, 1
	s_cmp_lg_u32 s0, s8
	s_cbranch_scc1 .Lgb4_wait
	buffer_wbl2 sc1
	s_waitcnt vmcnt(0)
	v_mov_b32_e32 v1, 1
	global_atomic_add v1, v0, v1, s[54:55] offset:1024 sc0
	s_waitcnt vmcnt(0)
	v_readfirstlane_b32 s0, v1
	s_add_u32 s0, s0, 1
	s_cmp_lg_u32 s0, s9
	s_cbranch_scc1 .Lgb4_wait
	v_mov_b32_e32 v1, 1
	global_atomic_add v0, v1, s[54:55] offset:1280
	s_waitcnt vmcnt(0)
	s_branch .LBB0_670

.Lgb4_spin:
	global_load_dword v1, v0, s[54:55] offset:1280 sc1
	s_waitcnt vmcnt(0)
	v_readfirstlane_b32 s0, v1
	s_cmp_ge_u32 s0, 4
	s_cbranch_scc1 .LBB0_670
	s_sleep 1
	s_add_u32 s1, s1, 1
	s_cmp_lt_u32 s1, 0x40000
	s_cbranch_scc1 .Lgb4_spin
	s_branch .LBB0_670

.LBB0_865:
	s_waitcnt vmcnt(0)
	s_barrier
	s_mov_b64 s[4:5], exec
	v_readlane_b32 s0, v255, 1
	v_readlane_b32 s1, v255, 2
	s_and_b64 s[0:1], s[4:5], s[0:1]
	s_mov_b64 exec, s[0:1]
	s_cbranch_execz .Lgb5_others
	s_getreg_b32 s0, hwreg(HW_REG_XCC_ID, 0, 4)
	v_mov_b32_e32 v0, 0x23fc0
	ds_read_b64 v[2:3], v0
	s_and_b32 s0, s0, 15
	s_lshl_b32 s0, s0, 8
	s_add_u32 s6, s54, s0
	s_addc_u32 s7, s55, 0
	v_mov_b32_e32 v0, 0x1000
	v_mov_b32_e32 v1, 1
	global_atomic_add v1, v0, v1, s[6:7] offset:1024 sc0
	s_waitcnt lgkmcnt(0)
	v_readfirstlane_b32 s8, v2
	v_readfirstlane_b32 s9, v3
	s_mul_i32 s8, s8, 5
	s_mul_i32 s9, s9, 5
	v_mov_b32_e32 v0, 0x3000
	s_waitcnt vmcnt(0)
	v_readfirstlane_b32 s0, v1
	s_add_u32 s0, s0, 1
	s_cmp_lg_u32 s0, s8
	s_cbranch_scc1 .Lgb5_wait
	buffer_wbl2 sc1
	s_waitcnt vmcnt(0)
	v_mov_b32_e32 v1, 1
	global_atomic_add v1, v0, v1, s[54:55] offset:1024 sc0
	s_waitcnt vmcnt(0)
	v_readfirstlane_b32 s0, v1
	s_add_u32 s0, s0, 1
	s_cmp_lg_u32 s0, s9
	s_cbranch_scc1 .Lgb5_wait
	v_mov_b32_e32 v1, 1
	global_atomic_add v0, v1, s[54:55] offset:1280
	s_waitcnt vmcnt(0)
	s_branch .LBB0_917

.Lgb5_spin:
	global_load_dword v1, v0, s[54:55] offset:1280 sc1
	s_waitcnt vmcnt(0)
	v_readfirstlane_b32 s0, v1
	s_cmp_ge_u32 s0, 5
	s_cbranch_scc1 .LBB0_917
	s_sleep 1
	s_add_u32 s1, s1, 1
	s_cmp_lt_u32 s1, 0x40000
	s_cbranch_scc1 .Lgb5_spin
	s_branch .LBB0_917

.LBB0_985:
	s_waitcnt vmcnt(0)
	s_waitcnt vmcnt(0)
	s_barrier
	s_mov_b64 s[4:5], exec
	v_readlane_b32 s0, v255, 1
	v_readlane_b32 s1, v255, 2
	s_and_b64 s[0:1], s[4:5], s[0:1]
	s_mov_b64 exec, s[0:1]
	s_cbranch_execz .Lgb6_others
	s_getreg_b32 s0, hwreg(HW_REG_XCC_ID, 0, 4)
	v_mov_b32_e32 v0, 0x23fc0
	ds_read_b64 v[2:3], v0
	s_and_b32 s0, s0, 15
	s_lshl_b32 s0, s0, 8
	s_add_u32 s6, s54, s0
	s_addc_u32 s7, s55, 0
	v_mov_b32_e32 v0, 0x1000
	v_mov_b32_e32 v1, 1
	global_atomic_add v1, v0, v1, s[6:7] offset:1024 sc0
	s_waitcnt lgkmcnt(0)
	v_readfirstlane_b32 s8, v2
	v_readfirstlane_b32 s9, v3
	s_mul_i32 s8, s8, 6
	s_mul_i32 s9, s9, 6
	v_mov_b32_e32 v0, 0x3000
	s_waitcnt vmcnt(0)
	v_readfirstlane_b32 s0, v1
	s_add_u32 s0, s0, 1
	s_cmp_lg_u32 s0, s8
	s_cbranch_scc1 .Lgb6_wait
	buffer_wbl2 sc1
	s_waitcnt vmcnt(0)
	v_mov_b32_e32 v1, 1
	global_atomic_add v1, v0, v1, s[54:55] offset:1024 sc0
	s_waitcnt vmcnt(0)
	v_readfirstlane_b32 s0, v1
	s_add_u32 s0, s0, 1
	s_cmp_lg_u32 s0, s9
	s_cbranch_scc1 .Lgb6_wait
	v_mov_b32_e32 v1, 1
	global_atomic_add v0, v1, s[54:55] offset:1280
	s_waitcnt vmcnt(0)
	s_branch .LBB0_1037

.Lgb6_spin:
	global_load_dword v1, v0, s[54:55] offset:1280 sc1
	s_waitcnt vmcnt(0)
	v_readfirstlane_b32 s0, v1
	s_cmp_ge_u32 s0, 6
	s_cbranch_scc1 .LBB0_1037
	s_sleep 1
	s_add_u32 s1, s1, 1
	s_cmp_lt_u32 s1, 0x40000
	s_cbranch_scc1 .Lgb6_spin
	s_branch .LBB0_1037
